# v14 + all three LayerNorm row loops: next-row wait in front of the row's last stores, no counter drain at the latch/top
# speedup vs baseline: 1.0080x; 1.0008x over previous
; DI void lnmod_phase(const Args& A, LAS unsigned char* lds, int tid, int bid, int G, bool init, int l_norm, int i_norm, int l_mod, int i_mod, bool want_dt, int nrows, bool ctx_partial, const float* gprev, const float* bprev) {
;     ...
;     u32x2 un[4]; f32x4 fn[4];
;     int mi_cur = -1; f32x4 shv[4], sclv[4];
;     { const int row = bid * 8 + wave;
;       if (row < nrows) {
;           if (init) { const float* xin = row < M_LAT ? A.in[I_X] + (size_t)row * DM : A.in[I_CTX] + (size_t)(row - M_LAT) * DM;
; #pragma unroll
;               for (int j = 0; j < 4; ++j) fn[j] = *(const f32x4*)(xin + 256 * j + 4 * lane); }
;           else {
; #pragma unroll
;               for (int j = 0; j < 4; ++j) un[j] = *(const u32x2*)(X16 + (size_t)row * DM + 256 * j + 4 * lane); } } }
;     for (int row = bid * 8 + wave; row < nrows; row += G * 8) {
.LBB0_201:
	v_ashrrev_i32_e32 v33, 6, v152
	v_readlane_b32 s6, v253, 33
	s_nop 1
	v_lshl_add_u32 v86, s6, 3, v33
	s_mov_b32 s6, 0x8800
	v_cmp_gt_i32_e32 vcc, s6, v86
	s_and_saveexec_b64 s[16:17], vcc
	s_cbranch_execz .LBB0_216
	v_ashrrev_i32_e32 v87, 31, v86
	v_readlane_b32 s6, v251, 45
	v_lshlrev_b64 v[64:65], 11, v[86:87]
	v_readlane_b32 s7, v251, 46
	v_lshlrev_b32_e32 v146, 3, v34
	v_mov_b32_e32 v33, v147
	v_lshl_add_u64 v[36:37], s[6:7], 0, v[64:65]
	v_lshl_add_u64 v[36:37], v[36:37], 0, v[146:147]
	global_load_dwordx2 v[92:93], v[36:37], off
	global_load_dwordx2 v[94:95], v[36:37], off offset:512
	global_load_dwordx2 v[98:99], v[36:37], off offset:1024
	global_load_dwordx2 v[88:89], v[36:37], off offset:1536
	v_readlane_b32 s6, v253, 34
	s_lshl_b32 s18, s6, 3
	v_lshl_add_u64 v[68:69], s[0:1], 0, v[32:33]
	v_lshl_add_u64 v[70:71], s[4:5], 0, v[32:33]
	v_add_u32_e32 v32, s18, v86
	v_ashrrev_i32_e32 v33, 31, v32
	v_lshlrev_b64 v[72:73], 11, v[32:33]
	v_lshlrev_b32_e32 v32, 3, v152
	v_lshlrev_b32_e32 v66, 2, v34
	v_cmp_eq_u32_e64 s[0:1], 0, v34
	v_lshl_add_u32 v67, v34, 6, 0
	v_and_b32_e32 v34, 0x1f8, v32
	v_mov_b64_e32 v[32:33], 0x240000
	v_readlane_b32 s4, v253, 35
	s_ashr_i32 s19, s18, 31
	v_lshl_add_u64 v[74:75], v[86:87], 3, v[32:33]
	v_mov_b64_e32 v[32:33], 0x400000
	s_and_b64 s[20:21], s[8:9], s[0:1]
	s_mul_hi_u32 s23, s4, 9
	s_mul_i32 s22, s4, 9
	v_or_b32_e32 v72, v72, v34
	s_lshl_b64 s[24:25], s[18:19], 11
	s_lshl_b64 s[26:27], s[18:19], 3
	v_lshl_add_u64 v[76:77], v[86:87], 4, v[32:33]
	s_lshl_b64 s[28:29], s[18:19], 4
	v_or_b32_e32 v64, v64, v34
	v_mov_b32_e32 v117, -1
	s_mov_b64 s[30:31], 0
	v_readlane_b32 s5, v253, 36
	s_waitcnt vmcnt(0)
	s_branch .LBB0_205

; DI float hlo(unsigned u) { return (float)__builtin_bit_cast(f16x2_t, u).x; }
; DI float hhi(unsigned u) { return (float)__builtin_bit_cast(f16x2_t, u).y; }
; DI void lnmod_phase(const Args& A, LAS unsigned char* lds, int tid, int bid, int G, bool init, int l_norm, int i_norm, int l_mod, int i_mod, bool want_dt, int nrows, bool ctx_partial, const float* gprev, const float* bprev) {
;     ...
;     for (int row = bid * 8 + wave; row < nrows; row += G * 8) {
;         bf16* xout = X16 + (size_t)row * DM;
;         f32x4 v[4];
; #pragma unroll
;         for (int j = 0; j < 4; ++j) v[j] = init ? fn[j] : (f32x4){hlo(un[j].x), hhi(un[j].x), hlo(un[j].y), hhi(un[j].y)};
;         { const int rown = row + G * 8;
;           if (rown < nrows) {
;               if (init) { const float* xin = rown < M_LAT ? A.in[I_X] + (size_t)rown * DM : A.in[I_CTX] + (size_t)(rown - M_LAT) * DM;
; #pragma unroll
;                   for (int j = 0; j < 4; ++j) fn[j] = *(const f32x4*)(xin + 256 * j + 4 * lane); }
;               else {
; #pragma unroll
;                   for (int j = 0; j < 4; ++j) un[j] = *(const u32x2*)(X16 + (size_t)rown * DM + 256 * j + 4 * lane); } } }
.LBB0_204:
	s_and_b64 s[4:5], exec, s[4:5]
	s_or_b64 s[30:31], s[4:5], s[30:31]
	v_lshl_add_u64 v[72:73], v[72:73], 0, s[24:25]
	v_lshl_add_u64 v[74:75], v[74:75], 0, s[26:27]
	v_lshl_add_u64 v[76:77], v[76:77], 0, s[28:29]
	v_lshl_add_u64 v[64:65], v[64:65], 0, s[24:25]
	s_waitcnt lgkmcnt(3)
	v_mov_b32_e32 v86, v116
	s_waitcnt lgkmcnt(1)
	v_mov_b32_e32 v92, v172
	s_waitcnt lgkmcnt(0)
	v_mov_b32_e32 v93, v173
	v_mov_b32_e32 v94, v174
	v_mov_b32_e32 v95, v175
	v_mov_b32_e32 v98, v176
	v_mov_b32_e32 v99, v177
	v_mov_b32_e32 v88, v178
	v_mov_b32_e32 v89, v179
	s_andn2_b64 exec, exec, s[30:31]
	s_cbranch_execz .LBB0_216
.LBB0_205:
	v_add_u32_e32 v116, s18, v86
	s_mov_b32 s4, 0x8800
	v_cmp_gt_i32_e32 vcc, s4, v116
	s_mov_b32 s4, 0x87ff
	v_cmp_lt_i32_e64 s[4:5], s4, v116
	v_mov_b32_e32 v78, v92
	v_mov_b32_e32 v79, v93
	v_mov_b32_e32 v80, v94
	v_mov_b32_e32 v81, v95
	v_mov_b32_e32 v82, v98
	v_mov_b32_e32 v83, v99
	v_mov_b32_e32 v84, v88
	v_mov_b32_e32 v85, v89
	s_and_saveexec_b64 s[6:7], vcc
	s_cbranch_execz .LBB0_207
	v_readlane_b32 s36, v253, 23
	v_readlane_b32 s38, v253, 25
	v_readlane_b32 s39, v253, 26
	v_readlane_b32 s37, v253, 24
	s_nop 0
	v_lshl_add_u64 v[78:79], s[38:39], 0, v[72:73]
	v_add_co_u32_e32 v84, vcc, 0x21200000, v78
	s_nop 1
	v_addc_co_u32_e32 v85, vcc, 0, v79, vcc
	global_load_dwordx2 v[78:79], v[84:85], off
	global_load_dwordx2 v[80:81], v[84:85], off offset:512
	global_load_dwordx2 v[82:83], v[84:85], off offset:1024
	s_nop 0
	global_load_dwordx2 v[84:85], v[84:85], off offset:1536

; DI void lnmod_phase(const Args& A, LAS unsigned char* lds, int tid, int bid, int G, bool init, int l_norm, int i_norm, int l_mod, int i_mod, bool want_dt, int nrows, bool ctx_partial, const float* gprev, const float* bprev) {
;     ...
;         if (l_mod >= 0) {
;             const int mi = row < M_LAT ? (row >> 12) : 8;
;             const float* mp = MOD + ((size_t)l_mod * 9 + mi) * 9216 + i_mod * 3072;
;             if (mi != mi_cur) { mi_cur = mi;
; #pragma unroll
;                 for (int j = 0; j < 4; ++j) { shv[j] = *(const f32x4*)(mp + 256 * j + 4 * lane); sclv[j] = *(const f32x4*)(mp + 1024 + 256 * j + 4 * lane) + 1.0f; } }
.LBB0_212:
	s_or_b64 exec, exec, s[6:7]
	s_waitcnt vmcnt(0)
	v_mov_b32_e32 v172, v78
	v_mov_b32_e32 v173, v79
	v_mov_b32_e32 v174, v80
	v_mov_b32_e32 v175, v81
	v_mov_b32_e32 v176, v82
	v_mov_b32_e32 v177, v83
	v_mov_b32_e32 v178, v84
	v_mov_b32_e32 v179, v85
	v_min_i32_e32 v86, 0x8000, v86
	v_ashrrev_i32_e32 v86, 12, v86
	v_cmp_ne_u32_e32 vcc, v86, v117
	s_and_saveexec_b64 s[6:7], vcc
	s_cbranch_execz .LBB0_214
	v_readlane_b32 s36, v251, 59
	v_ashrrev_i32_e32 v87, 31, v86
	v_readlane_b32 s37, v251, 60
	v_lshl_add_u64 v[32:33], s[22:23], 0, v[86:87]
	v_lshlrev_b32_e32 v146, 2, v66
	v_mov_b64_e32 v[34:35], s[36:37]
	v_mad_u64_u32 v[34:35], s[36:37], v32, s94, v[34:35]
	v_mad_i32_i24 v35, v33, s94, v35
	v_lshl_add_u64 v[32:33], v[34:35], 0, v[146:147]
	s_mov_b64 s[36:37], 0x1000
	v_lshl_add_u64 v[34:35], v[32:33], 0, s[36:37]
	global_load_dwordx4 v[48:51], v[34:35], off offset:1024
	global_load_dwordx4 v[52:55], v[34:35], off offset:2048
	s_movk_i32 s19, 0x1000
	v_add_co_u32_e32 v36, vcc, s19, v32
	v_mov_b32_e32 v117, v86
	s_nop 0
	v_addc_co_u32_e32 v37, vcc, 0, v33, vcc
	global_load_dwordx4 v[56:59], v[36:37], off
	global_load_dwordx4 v[60:63], v[34:35], off offset:3072
	global_load_dwordx4 v[44:47], v[32:33], off
	global_load_dwordx4 v[40:43], v[32:33], off offset:1024
	s_nop 0
	global_load_dwordx4 v[36:39], v[32:33], off offset:2048
	s_nop 0
	global_load_dwordx4 v[32:35], v[32:33], off offset:3072
	s_waitcnt vmcnt(7)
	v_pk_add_f32 v[50:51], v[50:51], 1.0 op_sel_hi:[1,0]
	v_pk_add_f32 v[48:49], v[48:49], 1.0 op_sel_hi:[1,0]
	s_waitcnt vmcnt(6)
	v_pk_add_f32 v[54:55], v[54:55], 1.0 op_sel_hi:[1,0]
	v_pk_add_f32 v[52:53], v[52:53], 1.0 op_sel_hi:[1,0]
	s_waitcnt vmcnt(5)
	v_pk_add_f32 v[58:59], v[58:59], 1.0 op_sel_hi:[1,0]
	v_pk_add_f32 v[56:57], v[56:57], 1.0 op_sel_hi:[1,0]
	s_waitcnt vmcnt(4)
	v_pk_add_f32 v[62:63], v[62:63], 1.0 op_sel_hi:[1,0]
	v_pk_add_f32 v[60:61], v[60:61], 1.0 op_sel_hi:[1,0]

; DI unsigned pkh2(float lo, float hi) { return __builtin_bit_cast(unsigned, __builtin_amdgcn_cvt_pkrtz(lo, hi)); }
; DI void lnmod_phase(const Args& A, LAS unsigned char* lds, int tid, int bid, int G, bool init, int l_norm, int i_norm, int l_mod, int i_mod, bool want_dt, int nrows, bool ctx_partial, const float* gprev, const float* bprev) {
;     ...
;         if (l_norm >= 0) {
;             float s = 0.f, s2 = 0.f;
; #pragma unroll
;             for (int j = 0; j < 4; ++j) { s += (v[j].x + v[j].y) + (v[j].z + v[j].w); s2 += (v[j].x * v[j].x + v[j].y * v[j].y) + (v[j].z * v[j].z + v[j].w * v[j].w); }
;             wave_sum2(s, s2);
;             const float mean = s * (1.f / DM);
;             const float rstd = 1.0f / sqrtf(fmaxf(s2 * (1.f / DM) - mean * mean, 0.f) + 1e-5f);
; #pragma unroll
;             for (int j = 0; j < 4; ++j) v[j] = v[j] - mean;
;             if (l_mod >= 0 && lane == 0) STAT[row] = (f32x2){mean, rstd};
; #pragma unroll
;             for (int j = 0; j < 4; ++j) v[j] = v[j] * rstd * g[j] + bb[j];
;         }
;         if (init && lane == 0) STAT[row] = (f32x2){0.f, 1.f};
;         if (init) {
; #pragma unroll
;             for (int j = 0; j < 4; ++j) { u32x2 w_; w_.x = pkh2(v[j].x, v[j].y); w_.y = pkh2(v[j].z, v[j].w); *(u32x2*)(xout + 256 * j + 4 * lane) = w_; }
;         }
;         if (l_norm >= 0 && l_mod < 0) {
; #pragma unroll
;             for (int j = 0; j < 4; ++j) *(f32x4*)(A.out + (size_t)row * DM + 256 * j + 4 * lane) = v[j];
;         }
;         if (l_mod >= 0) {
.Llnl1_bypass:
	s_waitcnt vmcnt(0)
	v_mov_b32_e32 v172, v78
	v_mov_b32_e32 v173, v79
	v_mov_b32_e32 v174, v80
	v_mov_b32_e32 v175, v81
	v_mov_b32_e32 v176, v82
	v_mov_b32_e32 v177, v83
	v_mov_b32_e32 v178, v84
	v_mov_b32_e32 v179, v85
	s_branch .LBB0_204

; DI void lnmod_phase(const Args& A, LAS unsigned char* lds, int tid, int bid, int G, bool init, int l_norm, int i_norm, int l_mod, int i_mod, bool want_dt, int nrows, bool ctx_partial, const float* gprev, const float* bprev) {
;     ...
;     u32x2 un[4]; f32x4 fn[4];
;     int mi_cur = -1; f32x4 shv[4], sclv[4];
;     { const int row = bid * 8 + wave;
;       if (row < nrows) {
;           if (init) { const float* xin = row < M_LAT ? A.in[I_X] + (size_t)row * DM : A.in[I_CTX] + (size_t)(row - M_LAT) * DM;
; #pragma unroll
;               for (int j = 0; j < 4; ++j) fn[j] = *(const f32x4*)(xin + 256 * j + 4 * lane); }
;           else {
; #pragma unroll
;               for (int j = 0; j < 4; ++j) un[j] = *(const u32x2*)(X16 + (size_t)row * DM + 256 * j + 4 * lane); } } }
;     for (int row = bid * 8 + wave; row < nrows; row += G * 8) {
.LBB0_276:
	v_ashrrev_i32_e32 v33, 6, v152
	v_readlane_b32 s1, v253, 33
	s_nop 1
	v_lshl_add_u32 v84, s1, 3, v33
	v_readlane_b32 s1, v253, 39
	s_nop 1
	v_cmp_gt_i32_e32 vcc, s1, v84
	s_and_saveexec_b64 s[6:7], vcc
	s_cbranch_execz .LBB0_289
	v_ashrrev_i32_e32 v85, 31, v84
	v_readlane_b32 s4, v251, 45
	v_lshlrev_b64 v[64:65], 11, v[84:85]
	v_readlane_b32 s5, v251, 46
	v_lshlrev_b32_e32 v146, 3, v34
	s_ashr_i32 s1, s0, 31
	v_lshl_add_u64 v[36:37], s[4:5], 0, v[64:65]
	v_lshl_add_u64 v[36:37], v[36:37], 0, v[146:147]
	global_load_dwordx2 v[90:91], v[36:37], off
	global_load_dwordx2 v[92:93], v[36:37], off offset:512
	global_load_dwordx2 v[96:97], v[36:37], off offset:1024
	global_load_dwordx2 v[86:87], v[36:37], off offset:1536
	v_readlane_b32 s16, v252, 54
	s_lshl_b64 s[0:1], s[0:1], 2
	v_readlane_b32 s28, v253, 2
	v_readlane_b32 s29, v253, 3
	s_add_u32 s4, s28, s0
	v_readlane_b32 s30, v253, 4
	s_addc_u32 s5, s29, s1
	v_readlane_b32 s31, v253, 5
	s_add_u32 s0, s30, s0
	v_readlane_b32 s8, v253, 34
	s_addc_u32 s1, s31, s1
	s_lshl_b32 s8, s8, 3
	v_mov_b32_e32 v33, v147
	v_lshl_add_u64 v[68:69], s[4:5], 0, v[32:33]
	v_lshl_add_u64 v[70:71], s[0:1], 0, v[32:33]
	v_add_u32_e32 v32, s8, v84
	v_ashrrev_i32_e32 v33, 31, v32
	v_lshlrev_b64 v[72:73], 11, v[32:33]
	v_lshlrev_b32_e32 v32, 3, v152
	v_readlane_b32 s17, v252, 55
	v_readlane_b32 s18, v252, 56
	v_readlane_b32 s19, v252, 57
	v_readlane_b32 s20, v252, 58
	v_readlane_b32 s21, v252, 59
	v_readlane_b32 s22, v252, 60
	v_readlane_b32 s23, v252, 61
	v_lshlrev_b32_e32 v66, 2, v34
	v_cmp_eq_u32_e32 vcc, 0, v34
	v_readlane_b32 s0, v253, 35
	v_and_b32_e32 v32, 0x1f8, v32
	s_ashr_i32 s9, s8, 31
	v_mov_b64_e32 v[34:35], 0x240000
	s_and_b64 s[14:15], s[2:3], vcc
	s_mul_hi_u32 s17, s0, 9
	s_mul_i32 s16, s0, 9
	v_or_b32_e32 v72, v72, v32
	s_lshl_b64 s[18:19], s[8:9], 11
	v_lshl_add_u64 v[74:75], v[84:85], 3, v[34:35]
	s_lshl_b64 s[20:21], s[8:9], 3
	v_or_b32_e32 v64, v64, v32
	v_mov_b32_e32 v85, -1
	s_mov_b64 s[22:23], 0
	v_readlane_b32 s24, v252, 62
	v_readlane_b32 s25, v252, 63
	v_readlane_b32 s26, v253, 0
	v_readlane_b32 s27, v253, 1
	v_readlane_b32 s1, v253, 36
	s_waitcnt vmcnt(0)
	s_branch .LBB0_280

; DI float hlo(unsigned u) { return (float)__builtin_bit_cast(f16x2_t, u).x; }
; DI float hhi(unsigned u) { return (float)__builtin_bit_cast(f16x2_t, u).y; }
; DI void lnmod_phase(const Args& A, LAS unsigned char* lds, int tid, int bid, int G, bool init, int l_norm, int i_norm, int l_mod, int i_mod, bool want_dt, int nrows, bool ctx_partial, const float* gprev, const float* bprev) {
;     ...
;     for (int row = bid * 8 + wave; row < nrows; row += G * 8) {
;         bf16* xout = X16 + (size_t)row * DM;
;         f32x4 v[4];
; #pragma unroll
;         for (int j = 0; j < 4; ++j) v[j] = init ? fn[j] : (f32x4){hlo(un[j].x), hhi(un[j].x), hlo(un[j].y), hhi(un[j].y)};
;         { const int rown = row + G * 8;
;           if (rown < nrows) {
;               if (init) { const float* xin = rown < M_LAT ? A.in[I_X] + (size_t)rown * DM : A.in[I_CTX] + (size_t)(rown - M_LAT) * DM;
; #pragma unroll
;                   for (int j = 0; j < 4; ++j) fn[j] = *(const f32x4*)(xin + 256 * j + 4 * lane); }
;               else {
; #pragma unroll
;                   for (int j = 0; j < 4; ++j) un[j] = *(const u32x2*)(X16 + (size_t)rown * DM + 256 * j + 4 * lane); } } }
.LBB0_279:
	s_and_b64 s[0:1], exec, s[0:1]
	s_or_b64 s[22:23], s[0:1], s[22:23]
	v_lshl_add_u64 v[72:73], v[72:73], 0, s[18:19]
	v_lshl_add_u64 v[74:75], v[74:75], 0, s[20:21]
	v_lshl_add_u64 v[64:65], v[64:65], 0, s[18:19]
	v_mov_b32_e32 v84, v67
	v_mov_b32_e32 v90, v124
	v_mov_b32_e32 v91, v125
	v_mov_b32_e32 v92, v126
	v_mov_b32_e32 v93, v127
	v_mov_b32_e32 v96, v128
	v_mov_b32_e32 v97, v129
	v_mov_b32_e32 v86, v130
	v_mov_b32_e32 v87, v131
	s_andn2_b64 exec, exec, s[22:23]
	s_cbranch_execz .LBB0_289
.LBB0_280:
	v_add_u32_e32 v67, s8, v84
	v_readlane_b32 s0, v253, 39
	v_mov_b32_e32 v76, v90
	v_mov_b32_e32 v77, v91
	v_cmp_gt_i32_e32 vcc, s0, v67
	v_cmp_le_i32_e64 s[0:1], s0, v67
	v_mov_b32_e32 v78, v92
	v_mov_b32_e32 v79, v93
	v_mov_b32_e32 v80, v96
	v_mov_b32_e32 v81, v97
	v_mov_b32_e32 v82, v86
	v_mov_b32_e32 v83, v87
	s_and_saveexec_b64 s[4:5], vcc
	s_cbranch_execz .LBB0_282
	v_readlane_b32 s24, v253, 23
	v_readlane_b32 s26, v253, 25
	v_readlane_b32 s27, v253, 26
	v_readlane_b32 s25, v253, 24
	s_nop 0
	v_lshl_add_u64 v[76:77], s[26:27], 0, v[72:73]
	v_add_co_u32_e32 v82, vcc, 0x21200000, v76
	s_nop 1
	v_addc_co_u32_e32 v83, vcc, 0, v77, vcc
	global_load_dwordx2 v[76:77], v[82:83], off
	global_load_dwordx2 v[78:79], v[82:83], off offset:512
	global_load_dwordx2 v[80:81], v[82:83], off offset:1024
	s_nop 0
	global_load_dwordx2 v[82:83], v[82:83], off offset:1536

; DI void lnmod_phase(const Args& A, LAS unsigned char* lds, int tid, int bid, int G, bool init, int l_norm, int i_norm, int l_mod, int i_mod, bool want_dt, int nrows, bool ctx_partial, const float* gprev, const float* bprev) {
;     ...
;         if (l_mod >= 0) {
;             const int mi = row < M_LAT ? (row >> 12) : 8;
;             const float* mp = MOD + ((size_t)l_mod * 9 + mi) * 9216 + i_mod * 3072;
;             if (mi != mi_cur) { mi_cur = mi;
; #pragma unroll
;                 for (int j = 0; j < 4; ++j) { shv[j] = *(const f32x4*)(mp + 256 * j + 4 * lane); sclv[j] = *(const f32x4*)(mp + 1024 + 256 * j + 4 * lane) + 1.0f; } }
.LBB0_287:
	s_or_b64 exec, exec, s[4:5]
	s_waitcnt vmcnt(0)
	v_mov_b32_e32 v124, v76
	v_mov_b32_e32 v125, v77
	v_mov_b32_e32 v126, v78
	v_mov_b32_e32 v127, v79
	v_mov_b32_e32 v128, v80
	v_mov_b32_e32 v129, v81
	v_mov_b32_e32 v130, v82
	v_mov_b32_e32 v131, v83
	v_min_i32_e32 v84, 0x8000, v84
	v_ashrrev_i32_e32 v84, 12, v84
	v_cmp_ne_u32_e32 vcc, v84, v85
	s_and_saveexec_b64 s[4:5], vcc
	s_cbranch_execz .LBB0_278
	v_readlane_b32 s24, v252, 7
	v_ashrrev_i32_e32 v85, 31, v84
	v_readlane_b32 s25, v252, 8
	v_lshl_add_u64 v[32:33], s[16:17], 0, v[84:85]
	v_lshlrev_b32_e32 v146, 2, v66
	v_mov_b64_e32 v[34:35], s[24:25]
	v_mad_u64_u32 v[34:35], s[24:25], v32, s94, v[34:35]
	v_mad_i32_i24 v35, v33, s94, v35
	v_lshl_add_u64 v[32:33], v[34:35], 0, v[146:147]
	s_mov_b64 s[24:25], 0x1000
	v_lshl_add_u64 v[34:35], v[32:33], 0, s[24:25]
	global_load_dwordx4 v[48:51], v[34:35], off offset:1024
	global_load_dwordx4 v[52:55], v[34:35], off offset:2048
	s_movk_i32 s9, 0x1000
	v_add_co_u32_e32 v36, vcc, s9, v32
	v_mov_b32_e32 v85, v84
	s_nop 0
	v_addc_co_u32_e32 v37, vcc, 0, v33, vcc
	global_load_dwordx4 v[56:59], v[36:37], off
	global_load_dwordx4 v[60:63], v[34:35], off offset:3072
	global_load_dwordx4 v[44:47], v[32:33], off
	global_load_dwordx4 v[40:43], v[32:33], off offset:1024
	s_nop 0
	global_load_dwordx4 v[36:39], v[32:33], off offset:2048
	s_nop 0
	global_load_dwordx4 v[32:35], v[32:33], off offset:3072
	s_waitcnt vmcnt(7)
	v_pk_add_f32 v[50:51], v[50:51], 1.0 op_sel_hi:[1,0]
	v_pk_add_f32 v[48:49], v[48:49], 1.0 op_sel_hi:[1,0]
	s_waitcnt vmcnt(6)
	v_pk_add_f32 v[54:55], v[54:55], 1.0 op_sel_hi:[1,0]
	v_pk_add_f32 v[52:53], v[52:53], 1.0 op_sel_hi:[1,0]
	s_waitcnt vmcnt(5)
	v_pk_add_f32 v[58:59], v[58:59], 1.0 op_sel_hi:[1,0]
	v_pk_add_f32 v[56:57], v[56:57], 1.0 op_sel_hi:[1,0]
	s_waitcnt vmcnt(4)
	v_pk_add_f32 v[62:63], v[62:63], 1.0 op_sel_hi:[1,0]
	v_pk_add_f32 v[60:61], v[60:61], 1.0 op_sel_hi:[1,0]
	s_branch .LBB0_278
.Llnl3_bypass:
	s_waitcnt vmcnt(0)
	v_mov_b32_e32 v124, v76
	v_mov_b32_e32 v125, v77
	v_mov_b32_e32 v126, v78
	v_mov_b32_e32 v127, v79
	v_mov_b32_e32 v128, v80
	v_mov_b32_e32 v129, v81
	v_mov_b32_e32 v130, v82
	v_mov_b32_e32 v131, v83
	s_branch .LBB0_279
